# combination: hand-written P8 epilogue + flips deleted + static prio waves 0-3 + peeled first K-iteration with C=0 (int8 loops) + head-of-segment lgkmcnt wait removed
# speedup vs baseline: 1.0057x; 1.0057x over previous
; #define PG8_STAGE(bufoff, gbase, voff) do { _Pragma("unroll") for (int _i = 0; _i < 2; ++_i) \
;         __builtin_amdgcn_global_load_lds((const unsigned*)((const char*)(gbase) + (voff)[_i]), (LAS unsigned*)(lds + (bufoff) + ldsw + _i * 8192), 16, 0, 0); } while (0)
; #define PG8_LDA(dst, b, h) do { _Pragma("unroll") for (int m = 0; m < 4; ++m) _Pragma("unroll") for (int k = 0; k < 2; ++k) dst[m][k] = *(const LAS bf16x8*)(lds + PG8_SA(b, h) + aoff + m * 2048 + k * 1024); } while (0)
; #define PG8_LDB(dst, b, h) do { _Pragma("unroll") for (int n = 0; n < 2; ++n) _Pragma("unroll") for (int k = 0; k < 2; ++k) dst[n][k] = *(const LAS bf16x8*)(lds + PG8_SB(b, h) + boff + n * 2048 + k * 1024); } while (0)
; #define PG8_WAIT_V(n) asm volatile("s_waitcnt vmcnt(" #n ")" ::: "memory")
; #define PG8_WAIT_L(n) asm volatile("s_waitcnt lgkmcnt(" #n ")" ::: "memory")
; #define PG8_BAR __builtin_amdgcn_s_barrier()
; #define PG8_SCHED __builtin_amdgcn_sched_barrier(0)
; template <class Epi, class Geom, class Sched, bool ALIGN_EPI, bool I8 = false>
; __device__ __forceinline__ void gemm_phase(LAS unsigned char* lds, const Gemm g, const Sched& S, const Epi& E) {
;     ...
;             PG8_LDB(B0, 0, 0); PG8_LDB(B1, 0, 1); PG8_SCHED; PG8_LDA(At, 0, 0); PG8_STAGE(PG8_SA(1, 1), a1 + hsA, voffA);
;             PG8_WAIT_V(8); PG8_WAIT_L(0); PG8_BAR; PG8_MMA(0, 0, At, B0); PG8_MMA(0, 1, At, B1); PG8_BAR; PG8_SCHED;
;             PG8_LDA(At, 0, 1); PG8_STAGE(PG8_SB(0, 0), b2, voffB); PG8_STAGE(PG8_SB(0, 1), b2 + hsB, voffB); PG8_STAGE(PG8_SA(0, 0), a2, voffA);
;             PG8_WAIT_V(8); PG8_WAIT_L(0); PG8_BAR; PG8_MMA(1, 0, At, B0); PG8_MMA(1, 1, At, B1); PG8_BAR; PG8_SCHED;
.Lpz1_0:
	ds_read_b128 v[102:105], v166
	ds_read_b128 v[106:109], v166 offset:1024
	ds_read_b128 v[114:117], v166 offset:2048
	ds_read_b128 v[118:121], v166 offset:3072
	ds_read_b128 v[156:159], v167
	ds_read_b128 v[170:173], v167 offset:1024
	ds_read_b128 v[174:177], v167 offset:2048
	ds_read_b128 v[178:181], v167 offset:3072
	s_add_u32 s34, s30, 0xfff80080
	s_addc_u32 s35, s31, -1
	s_cmp_eq_u32 s61, 28
	s_cselect_b32 s37, s23, s35
	s_cselect_b32 s36, s57, s34
	s_cselect_b32 s35, s21, s60
	s_cselect_b32 s34, s58, s59
	v_lshl_add_u64 v[160:161], s[30:31], 0, v[150:151]
	s_add_i32 m0, s29, 0xc000
	ds_read_b128 v[182:185], v168
	ds_read_b128 v[186:189], v168 offset:1024
	ds_read_b128 v[190:193], v168 offset:2048
	ds_read_b128 v[194:197], v168 offset:3072
	ds_read_b128 v[198:201], v168 offset:4096
	ds_read_b128 v[202:205], v168 offset:5120
	ds_read_b128 v[206:209], v168 offset:6144
	ds_read_b128 v[210:213], v168 offset:7168
	global_load_lds_dwordx4 v[160:161], off
	v_lshl_add_u64 v[160:161], s[30:31], 0, v[152:153]
	s_add_i32 m0, s29, 0xe000
	s_nop 0
	global_load_lds_dwordx4 v[160:161], off
	s_waitcnt vmcnt(8)
	s_waitcnt lgkmcnt(0)
	s_barrier
	v_mfma_i32_16x16x64_i8 v[142:145], v[102:105], v[182:185], 0
	v_mfma_i32_16x16x64_i8 v[138:141], v[114:117], v[182:185], 0
	v_mfma_i32_16x16x64_i8 v[126:129], v[102:105], v[190:193], 0
	v_mfma_i32_16x16x64_i8 v[122:125], v[114:117], v[190:193], 0
	v_mfma_i32_16x16x64_i8 v[94:97], v[102:105], v[198:201], 0
	v_mfma_i32_16x16x64_i8 v[90:93], v[114:117], v[198:201], 0
	v_mfma_i32_16x16x64_i8 v[82:85], v[102:105], v[206:209], 0
	v_mfma_i32_16x16x64_i8 v[74:77], v[114:117], v[206:209], 0
	v_mfma_i32_16x16x64_i8 v[142:145], v[106:109], v[186:189], v[142:145]
	v_mfma_i32_16x16x64_i8 v[138:141], v[118:121], v[186:189], v[138:141]
	v_mfma_i32_16x16x64_i8 v[126:129], v[106:109], v[194:197], v[126:129]
	v_mfma_i32_16x16x64_i8 v[122:125], v[118:121], v[194:197], v[122:125]
	v_mfma_i32_16x16x64_i8 v[94:97], v[106:109], v[202:205], v[94:97]
	v_mfma_i32_16x16x64_i8 v[90:93], v[118:121], v[202:205], v[90:93]
	v_mfma_i32_16x16x64_i8 v[82:85], v[106:109], v[210:213], v[82:85]
	v_mfma_i32_16x16x64_i8 v[74:77], v[118:121], v[210:213], v[74:77]
	v_mfma_i32_16x16x64_i8 v[134:137], v[156:159], v[182:185], 0
	v_mfma_i32_16x16x64_i8 v[130:133], v[174:177], v[182:185], 0
	v_mfma_i32_16x16x64_i8 v[110:113], v[156:159], v[190:193], 0
	v_mfma_i32_16x16x64_i8 v[98:101], v[174:177], v[190:193], 0
	v_mfma_i32_16x16x64_i8 v[86:89], v[156:159], v[198:201], 0
	v_mfma_i32_16x16x64_i8 v[78:81], v[174:177], v[198:201], 0
	v_mfma_i32_16x16x64_i8 v[70:73], v[156:159], v[206:209], 0
	v_mfma_i32_16x16x64_i8 v[66:69], v[174:177], v[206:209], 0
	v_mfma_i32_16x16x64_i8 v[134:137], v[170:173], v[186:189], v[134:137]
	v_mfma_i32_16x16x64_i8 v[130:133], v[178:181], v[186:189], v[130:133]
	v_mfma_i32_16x16x64_i8 v[110:113], v[170:173], v[194:197], v[110:113]
	v_mfma_i32_16x16x64_i8 v[98:101], v[178:181], v[194:197], v[98:101]
	v_mfma_i32_16x16x64_i8 v[86:89], v[170:173], v[202:205], v[86:89]
	v_mfma_i32_16x16x64_i8 v[78:81], v[178:181], v[202:205], v[78:81]
	v_mfma_i32_16x16x64_i8 v[70:73], v[170:173], v[210:213], v[70:73]
	v_mfma_i32_16x16x64_i8 v[66:69], v[178:181], v[210:213], v[66:69]
	s_barrier
	s_add_i32 s62, s10, s41
	v_lshl_add_u64 v[160:161], s[34:35], 0, v[146:147]
	s_mov_b32 m0, s62
	ds_read_b128 v[182:185], v168 offset:16384
	ds_read_b128 v[186:189], v168 offset:17408
	ds_read_b128 v[190:193], v168 offset:18432
	ds_read_b128 v[194:197], v168 offset:19456
	ds_read_b128 v[198:201], v168 offset:20480
	ds_read_b128 v[202:205], v168 offset:21504
	ds_read_b128 v[206:209], v168 offset:22528
	ds_read_b128 v[210:213], v168 offset:23552
	global_load_lds_dwordx4 v[160:161], off
	s_add_i32 m0, s62, 0x2000
	s_add_u32 s62, s34, 0x80000
	v_lshl_add_u64 v[214:215], s[34:35], 0, v[148:149]
	s_addc_u32 s63, s35, 0
	s_add_i32 s64, s50, s41
	global_load_lds_dwordx4 v[214:215], off
	v_lshl_add_u64 v[216:217], s[62:63], 0, v[146:147]
	s_mov_b32 m0, s64
	v_lshl_add_u64 v[218:219], s[36:37], 0, v[148:149]
	global_load_lds_dwordx4 v[216:217], off
	v_lshl_add_u64 v[216:217], s[62:63], 0, v[148:149]
	s_add_i32 m0, s64, 0x2000
	s_nop 0
	global_load_lds_dwordx4 v[216:217], off
	v_lshl_add_u64 v[216:217], s[36:37], 0, v[146:147]
	s_mov_b32 m0, s29
	s_nop 0
	global_load_lds_dwordx4 v[216:217], off
	s_mov_b32 m0, s44
	s_nop 0
	global_load_lds_dwordx4 v[218:219], off
	s_waitcnt vmcnt(8)
	s_waitcnt lgkmcnt(0)
	s_barrier
	v_mfma_i32_16x16x64_i8 v[62:65], v[102:105], v[182:185], 0
	v_mfma_i32_16x16x64_i8 v[58:61], v[114:117], v[182:185], 0
	v_mfma_i32_16x16x64_i8 v[50:53], v[102:105], v[190:193], 0
	v_mfma_i32_16x16x64_i8 v[42:45], v[114:117], v[190:193], 0
	v_mfma_i32_16x16x64_i8 v[30:33], v[102:105], v[198:201], 0
	v_mfma_i32_16x16x64_i8 v[26:29], v[114:117], v[198:201], 0
	v_mfma_i32_16x16x64_i8 v[18:21], v[102:105], v[206:209], 0
	v_mfma_i32_16x16x64_i8 v[10:13], v[114:117], v[206:209], 0
	v_mfma_i32_16x16x64_i8 v[62:65], v[106:109], v[186:189], v[62:65]
	v_mfma_i32_16x16x64_i8 v[58:61], v[118:121], v[186:189], v[58:61]
	v_mfma_i32_16x16x64_i8 v[50:53], v[106:109], v[194:197], v[50:53]
	v_mfma_i32_16x16x64_i8 v[42:45], v[118:121], v[194:197], v[42:45]
	v_mfma_i32_16x16x64_i8 v[30:33], v[106:109], v[202:205], v[30:33]
	v_mfma_i32_16x16x64_i8 v[26:29], v[118:121], v[202:205], v[26:29]
	v_mfma_i32_16x16x64_i8 v[18:21], v[106:109], v[210:213], v[18:21]
	v_mfma_i32_16x16x64_i8 v[10:13], v[118:121], v[210:213], v[10:13]
	v_mfma_i32_16x16x64_i8 v[54:57], v[156:159], v[182:185], 0
	v_mfma_i32_16x16x64_i8 v[46:49], v[174:177], v[182:185], 0
	v_mfma_i32_16x16x64_i8 v[38:41], v[156:159], v[190:193], 0
	v_mfma_i32_16x16x64_i8 v[34:37], v[174:177], v[190:193], 0
	v_mfma_i32_16x16x64_i8 v[22:25], v[156:159], v[198:201], 0
	v_mfma_i32_16x16x64_i8 v[14:17], v[174:177], v[198:201], 0
	v_mfma_i32_16x16x64_i8 v[6:9], v[156:159], v[206:209], 0
	v_mfma_i32_16x16x64_i8 v[2:5], v[174:177], v[206:209], 0
	v_mfma_i32_16x16x64_i8 v[54:57], v[170:173], v[186:189], v[54:57]
	v_mfma_i32_16x16x64_i8 v[46:49], v[178:181], v[186:189], v[46:49]
	v_mfma_i32_16x16x64_i8 v[38:41], v[170:173], v[194:197], v[38:41]
	v_mfma_i32_16x16x64_i8 v[34:37], v[178:181], v[194:197], v[34:37]
	v_mfma_i32_16x16x64_i8 v[22:25], v[170:173], v[202:205], v[22:25]
	v_mfma_i32_16x16x64_i8 v[14:17], v[178:181], v[202:205], v[14:17]
	v_mfma_i32_16x16x64_i8 v[6:9], v[170:173], v[210:213], v[6:9]
	v_mfma_i32_16x16x64_i8 v[2:5], v[178:181], v[210:213], v[2:5]
	s_barrier
; #define PG8_STAGE(bufoff, gbase, voff) do { _Pragma("unroll") for (int _i = 0; _i < 2; ++_i) \
;         __builtin_amdgcn_global_load_lds((const unsigned*)((const char*)(gbase) + (voff)[_i]), (LAS unsigned*)(lds + (bufoff) + ldsw + _i * 8192), 16, 0, 0); } while (0)
; #define PG8_LDA(dst, b, h) do { _Pragma("unroll") for (int m = 0; m < 4; ++m) _Pragma("unroll") for (int k = 0; k < 2; ++k) dst[m][k] = *(const LAS bf16x8*)(lds + PG8_SA(b, h) + aoff + m * 2048 + k * 1024); } while (0)
; #define PG8_LDB(dst, b, h) do { _Pragma("unroll") for (int n = 0; n < 2; ++n) _Pragma("unroll") for (int k = 0; k < 2; ++k) dst[n][k] = *(const LAS bf16x8*)(lds + PG8_SB(b, h) + boff + n * 2048 + k * 1024); } while (0)
; #define PG8_WAIT_V(n) asm volatile("s_waitcnt vmcnt(" #n ")" ::: "memory")
; #define PG8_WAIT_L(n) asm volatile("s_waitcnt lgkmcnt(" #n ")" ::: "memory")
; #define PG8_BAR __builtin_amdgcn_s_barrier()
; #define PG8_SCHED __builtin_amdgcn_sched_barrier(0)
; template <class Epi, class Geom, class Sched, bool ALIGN_EPI, bool I8 = false>
; __device__ __forceinline__ void gemm_phase(LAS unsigned char* lds, const Gemm g, const Sched& S, const Epi& E) {
;     ...
;             PG8_LDB(B0, 1, 0); PG8_LDB(B1, 1, 1); PG8_SCHED; PG8_LDA(At, 1, 0); PG8_STAGE(PG8_SA(0, 1), a2 + hsA, voffA);
;             PG8_WAIT_V(8); PG8_WAIT_L(0); PG8_BAR; PG8_MMA(0, 0, At, B0); PG8_MMA(0, 1, At, B1); PG8_BAR; PG8_SCHED;
;             PG8_LDA(At, 1, 1); PG8_STAGE(PG8_SB(1, 0), b3, voffB); PG8_STAGE(PG8_SB(1, 1), b3 + hsB, voffB); PG8_STAGE(PG8_SA(1, 0), a3, voffA);
;             PG8_WAIT_V(8); PG8_WAIT_L(0); PG8_BAR; PG8_MMA(1, 0, At, B0); PG8_MMA(1, 1, At, B1); PG8_BAR; PG8_SCHED;
;         }
	s_add_i32 s62, 0, 0x18000
	s_add_i32 s63, 0, 0x1c000
	v_add_u32_e32 v118, s62, v164
	v_add_u32_e32 v162, s63, v164
	ds_read_b128 v[102:105], v118
	ds_read_b128 v[106:109], v118 offset:1024
	ds_read_b128 v[114:117], v118 offset:2048
	ds_read_b128 v[118:121], v118 offset:3072
	ds_read_b128 v[156:159], v162
	ds_read_b128 v[170:173], v162 offset:1024
	ds_read_b128 v[174:177], v162 offset:2048
	ds_read_b128 v[178:181], v162 offset:3072
	s_add_u32 s36, s36, 0x80000
	s_addc_u32 s37, s37, 0
	s_mov_b32 m0, s45
	v_lshl_add_u64 v[220:221], s[36:37], 0, v[146:147]
	ds_read_b128 v[182:185], v168 offset:32768
	ds_read_b128 v[186:189], v168 offset:33792
	ds_read_b128 v[190:193], v168 offset:34816
	ds_read_b128 v[194:197], v168 offset:35840
	ds_read_b128 v[198:201], v168 offset:36864
	ds_read_b128 v[202:205], v168 offset:37888
	ds_read_b128 v[206:209], v168 offset:38912
	ds_read_b128 v[210:213], v168 offset:39936
	global_load_lds_dwordx4 v[220:221], off
	v_lshl_add_u64 v[220:221], s[36:37], 0, v[148:149]
	s_mov_b32 m0, s46
	s_nop 0
	global_load_lds_dwordx4 v[220:221], off
	s_waitcnt vmcnt(8)
	s_waitcnt lgkmcnt(0)
	s_barrier
	v_mfma_i32_16x16x64_i8 v[142:145], v[102:105], v[182:185], v[142:145]
	v_mfma_i32_16x16x64_i8 v[138:141], v[114:117], v[182:185], v[138:141]
	v_mfma_i32_16x16x64_i8 v[126:129], v[102:105], v[190:193], v[126:129]
	v_mfma_i32_16x16x64_i8 v[122:125], v[114:117], v[190:193], v[122:125]
	v_mfma_i32_16x16x64_i8 v[94:97], v[102:105], v[198:201], v[94:97]
	v_mfma_i32_16x16x64_i8 v[90:93], v[114:117], v[198:201], v[90:93]
	v_mfma_i32_16x16x64_i8 v[82:85], v[102:105], v[206:209], v[82:85]
	v_mfma_i32_16x16x64_i8 v[74:77], v[114:117], v[206:209], v[74:77]
	v_mfma_i32_16x16x64_i8 v[142:145], v[106:109], v[186:189], v[142:145]
	v_mfma_i32_16x16x64_i8 v[138:141], v[118:121], v[186:189], v[138:141]
	v_mfma_i32_16x16x64_i8 v[126:129], v[106:109], v[194:197], v[126:129]
	v_mfma_i32_16x16x64_i8 v[122:125], v[118:121], v[194:197], v[122:125]
	v_mfma_i32_16x16x64_i8 v[94:97], v[106:109], v[202:205], v[94:97]
	v_mfma_i32_16x16x64_i8 v[90:93], v[118:121], v[202:205], v[90:93]
	v_mfma_i32_16x16x64_i8 v[82:85], v[106:109], v[210:213], v[82:85]
	v_mfma_i32_16x16x64_i8 v[74:77], v[118:121], v[210:213], v[74:77]
	v_mfma_i32_16x16x64_i8 v[134:137], v[156:159], v[182:185], v[134:137]
	v_mfma_i32_16x16x64_i8 v[130:133], v[174:177], v[182:185], v[130:133]
	v_mfma_i32_16x16x64_i8 v[110:113], v[156:159], v[190:193], v[110:113]
	v_mfma_i32_16x16x64_i8 v[98:101], v[174:177], v[190:193], v[98:101]
	v_mfma_i32_16x16x64_i8 v[86:89], v[156:159], v[198:201], v[86:89]
	v_mfma_i32_16x16x64_i8 v[78:81], v[174:177], v[198:201], v[78:81]
	v_mfma_i32_16x16x64_i8 v[70:73], v[156:159], v[206:209], v[70:73]
	v_mfma_i32_16x16x64_i8 v[66:69], v[174:177], v[206:209], v[66:69]
	v_mfma_i32_16x16x64_i8 v[134:137], v[170:173], v[186:189], v[134:137]
	v_mfma_i32_16x16x64_i8 v[130:133], v[178:181], v[186:189], v[130:133]
	v_mfma_i32_16x16x64_i8 v[110:113], v[170:173], v[194:197], v[110:113]
	v_mfma_i32_16x16x64_i8 v[98:101], v[178:181], v[194:197], v[98:101]
	v_mfma_i32_16x16x64_i8 v[86:89], v[170:173], v[202:205], v[86:89]
	v_mfma_i32_16x16x64_i8 v[78:81], v[178:181], v[202:205], v[78:81]
	v_mfma_i32_16x16x64_i8 v[70:73], v[170:173], v[210:213], v[70:73]
	v_mfma_i32_16x16x64_i8 v[66:69], v[178:181], v[210:213], v[66:69]
	s_barrier
	s_add_i32 s36, s62, s41
	v_lshl_add_u64 v[160:161], v[160:161], 0, s[16:17]
	s_mov_b32 m0, s36
	ds_read_b128 v[182:185], v168 offset:49152
	ds_read_b128 v[186:189], v168 offset:50176
	ds_read_b128 v[190:193], v168 offset:51200
	ds_read_b128 v[194:197], v168 offset:52224
	ds_read_b128 v[198:201], v168 offset:53248
	ds_read_b128 v[202:205], v168 offset:54272
	ds_read_b128 v[206:209], v168 offset:55296
	ds_read_b128 v[210:213], v168 offset:56320
	global_load_lds_dwordx4 v[160:161], off
	s_add_i32 m0, s36, 0x2000
	s_add_u32 s34, s34, 0x80080
	v_lshl_add_u64 v[160:161], v[214:215], 0, s[16:17]
	s_addc_u32 s35, s35, 0
	s_add_i32 s36, s63, s41
	global_load_lds_dwordx4 v[160:161], off
	v_lshl_add_u64 v[160:161], s[34:35], 0, v[146:147]
	s_mov_b32 m0, s36
	s_nop 0
	global_load_lds_dwordx4 v[160:161], off
	v_lshl_add_u64 v[160:161], s[34:35], 0, v[148:149]
	s_add_i32 m0, s36, 0x2000
	s_nop 0
	global_load_lds_dwordx4 v[160:161], off
	v_lshl_add_u64 v[160:161], v[216:217], 0, s[16:17]
	s_mov_b32 m0, s47
	s_nop 0
	global_load_lds_dwordx4 v[160:161], off
	v_lshl_add_u64 v[160:161], v[218:219], 0, s[16:17]
	s_mov_b32 m0, s48
	s_nop 0
	global_load_lds_dwordx4 v[160:161], off
	s_waitcnt vmcnt(8)
	s_waitcnt lgkmcnt(0)
	s_barrier
	v_mfma_i32_16x16x64_i8 v[62:65], v[102:105], v[182:185], v[62:65]
	v_mfma_i32_16x16x64_i8 v[58:61], v[114:117], v[182:185], v[58:61]
	v_mfma_i32_16x16x64_i8 v[50:53], v[102:105], v[190:193], v[50:53]
	v_mfma_i32_16x16x64_i8 v[42:45], v[114:117], v[190:193], v[42:45]
	v_mfma_i32_16x16x64_i8 v[30:33], v[102:105], v[198:201], v[30:33]
	v_mfma_i32_16x16x64_i8 v[26:29], v[114:117], v[198:201], v[26:29]
	v_mfma_i32_16x16x64_i8 v[18:21], v[102:105], v[206:209], v[18:21]
	v_mfma_i32_16x16x64_i8 v[10:13], v[114:117], v[206:209], v[10:13]
	v_mfma_i32_16x16x64_i8 v[62:65], v[106:109], v[186:189], v[62:65]
	v_mfma_i32_16x16x64_i8 v[58:61], v[118:121], v[186:189], v[58:61]
	v_mfma_i32_16x16x64_i8 v[50:53], v[106:109], v[194:197], v[50:53]
	v_mfma_i32_16x16x64_i8 v[42:45], v[118:121], v[194:197], v[42:45]
	v_mfma_i32_16x16x64_i8 v[30:33], v[106:109], v[202:205], v[30:33]
	v_mfma_i32_16x16x64_i8 v[26:29], v[118:121], v[202:205], v[26:29]
	v_mfma_i32_16x16x64_i8 v[18:21], v[106:109], v[210:213], v[18:21]
	v_mfma_i32_16x16x64_i8 v[10:13], v[118:121], v[210:213], v[10:13]
	v_mfma_i32_16x16x64_i8 v[54:57], v[156:159], v[182:185], v[54:57]
	v_mfma_i32_16x16x64_i8 v[46:49], v[174:177], v[182:185], v[46:49]
	v_mfma_i32_16x16x64_i8 v[38:41], v[156:159], v[190:193], v[38:41]
	v_mfma_i32_16x16x64_i8 v[34:37], v[174:177], v[190:193], v[34:37]
	v_mfma_i32_16x16x64_i8 v[22:25], v[156:159], v[198:201], v[22:25]
	v_mfma_i32_16x16x64_i8 v[14:17], v[174:177], v[198:201], v[14:17]
	v_mfma_i32_16x16x64_i8 v[6:9], v[156:159], v[206:209], v[6:9]
	v_mfma_i32_16x16x64_i8 v[2:5], v[174:177], v[206:209], v[2:5]
	v_mfma_i32_16x16x64_i8 v[54:57], v[170:173], v[186:189], v[54:57]
	v_mfma_i32_16x16x64_i8 v[46:49], v[178:181], v[186:189], v[46:49]
	v_mfma_i32_16x16x64_i8 v[38:41], v[170:173], v[194:197], v[38:41]
	v_mfma_i32_16x16x64_i8 v[34:37], v[178:181], v[194:197], v[34:37]
	v_mfma_i32_16x16x64_i8 v[22:25], v[170:173], v[202:205], v[22:25]
	v_mfma_i32_16x16x64_i8 v[14:17], v[178:181], v[202:205], v[14:17]
	v_mfma_i32_16x16x64_i8 v[6:9], v[170:173], v[210:213], v[6:9]
	v_mfma_i32_16x16x64_i8 v[2:5], v[178:181], v[210:213], v[2:5]
	s_barrier
	s_add_i32 s61, s61, 2
	s_add_u32 s30, s30, 0x100
	s_addc_u32 s31, s31, 0
	s_add_u32 s59, s59, 0x100
	s_addc_u32 s60, s60, 0
	s_cmp_gt_u32 s61, 29
	s_branch .LBB0_2231

; #define PG8_STAGE(bufoff, gbase, voff) do { _Pragma("unroll") for (int _i = 0; _i < 2; ++_i) \
;         __builtin_amdgcn_global_load_lds((const unsigned*)((const char*)(gbase) + (voff)[_i]), (LAS unsigned*)(lds + (bufoff) + ldsw + _i * 8192), 16, 0, 0); } while (0)
; #define PG8_LDA(dst, b, h) do { _Pragma("unroll") for (int m = 0; m < 4; ++m) _Pragma("unroll") for (int k = 0; k < 2; ++k) dst[m][k] = *(const LAS bf16x8*)(lds + PG8_SA(b, h) + aoff + m * 2048 + k * 1024); } while (0)
; #define PG8_LDB(dst, b, h) do { _Pragma("unroll") for (int n = 0; n < 2; ++n) _Pragma("unroll") for (int k = 0; k < 2; ++k) dst[n][k] = *(const LAS bf16x8*)(lds + PG8_SB(b, h) + boff + n * 2048 + k * 1024); } while (0)
; #define PG8_WAIT_V(n) asm volatile("s_waitcnt vmcnt(" #n ")" ::: "memory")
; #define PG8_WAIT_L(n) asm volatile("s_waitcnt lgkmcnt(" #n ")" ::: "memory")
; #define PG8_BAR __builtin_amdgcn_s_barrier()
; #define PG8_SCHED __builtin_amdgcn_sched_barrier(0)
; template <class Epi, class Geom, class Sched, bool ALIGN_EPI, bool I8 = false>
; __device__ __forceinline__ void gemm_phase(LAS unsigned char* lds, const Gemm g, const Sched& S, const Epi& E) {
;     ...
;             PG8_LDB(B0, 0, 0); PG8_LDB(B1, 0, 1); PG8_SCHED; PG8_LDA(At, 0, 0); PG8_STAGE(PG8_SA(1, 1), a1 + hsA, voffA);
;             PG8_WAIT_V(8); PG8_WAIT_L(0); PG8_BAR; PG8_MMA(0, 0, At, B0); PG8_MMA(0, 1, At, B1); PG8_BAR; PG8_SCHED;
;             PG8_LDA(At, 0, 1); PG8_STAGE(PG8_SB(0, 0), b2, voffB); PG8_STAGE(PG8_SB(0, 1), b2 + hsB, voffB); PG8_STAGE(PG8_SA(0, 0), a2, voffA);
;             PG8_WAIT_V(8); PG8_WAIT_L(0); PG8_BAR; PG8_MMA(1, 0, At, B0); PG8_MMA(1, 1, At, B1); PG8_BAR; PG8_SCHED;
.Lpz0_0:
	ds_read_b128 v[130:133], v248
	ds_read_b128 v[134:137], v248 offset:1024
	ds_read_b128 v[138:141], v248 offset:2048
	ds_read_b128 v[142:145], v248 offset:3072
	ds_read_b128 v[146:149], v249
	ds_read_b128 v[150:153], v249 offset:1024
	ds_read_b128 v[154:157], v249 offset:2048
	ds_read_b128 v[158:161], v249 offset:3072
	s_add_u32 s62, s20, 0xfff80080
	s_addc_u32 s63, s21, -1
	s_cmp_eq_u32 s69, 28
	s_cselect_b32 s67, s3, s63
	s_cselect_b32 s66, s33, s62
	s_cselect_b32 s63, s55, s68
	s_cselect_b32 s62, s57, s65
	v_lshl_add_u64 v[166:167], s[20:21], 0, v[182:183]
	s_add_i32 m0, s78, 0xc000
	ds_read_b128 v[162:165], v250
	ds_read_b128 v[190:193], v250 offset:1024
	ds_read_b128 v[194:197], v250 offset:2048
	ds_read_b128 v[198:201], v250 offset:3072
	ds_read_b128 v[202:205], v250 offset:4096
	ds_read_b128 v[206:209], v250 offset:5120
	ds_read_b128 v[210:213], v250 offset:6144
	ds_read_b128 v[214:217], v250 offset:7168
	global_load_lds_dwordx4 v[166:167], off
	v_lshl_add_u64 v[166:167], s[20:21], 0, v[184:185]
	s_add_i32 m0, s78, 0xe000
	s_nop 0
	global_load_lds_dwordx4 v[166:167], off
	s_waitcnt vmcnt(8)
	s_waitcnt lgkmcnt(0)
	s_barrier
	v_mfma_i32_16x16x64_i8 v[126:129], v[130:133], v[162:165], 0
	v_mfma_i32_16x16x64_i8 v[122:125], v[138:141], v[162:165], 0
	v_mfma_i32_16x16x64_i8 v[114:117], v[130:133], v[194:197], 0
	v_mfma_i32_16x16x64_i8 v[106:109], v[138:141], v[194:197], 0
	v_mfma_i32_16x16x64_i8 v[102:105], v[130:133], v[202:205], 0
	v_mfma_i32_16x16x64_i8 v[94:97], v[138:141], v[202:205], 0
	v_mfma_i32_16x16x64_i8 v[86:89], v[130:133], v[210:213], 0
	v_mfma_i32_16x16x64_i8 v[78:81], v[138:141], v[210:213], 0
	v_mfma_i32_16x16x64_i8 v[126:129], v[134:137], v[190:193], v[126:129]
	v_mfma_i32_16x16x64_i8 v[122:125], v[142:145], v[190:193], v[122:125]
	v_mfma_i32_16x16x64_i8 v[114:117], v[134:137], v[198:201], v[114:117]
	v_mfma_i32_16x16x64_i8 v[106:109], v[142:145], v[198:201], v[106:109]
	v_mfma_i32_16x16x64_i8 v[102:105], v[134:137], v[206:209], v[102:105]
	v_mfma_i32_16x16x64_i8 v[94:97], v[142:145], v[206:209], v[94:97]
	v_mfma_i32_16x16x64_i8 v[86:89], v[134:137], v[214:217], v[86:89]
	v_mfma_i32_16x16x64_i8 v[78:81], v[142:145], v[214:217], v[78:81]
	v_mfma_i32_16x16x64_i8 v[118:121], v[146:149], v[162:165], 0
	v_mfma_i32_16x16x64_i8 v[82:85], v[154:157], v[162:165], 0
	v_mfma_i32_16x16x64_i8 v[110:113], v[146:149], v[194:197], 0
	v_mfma_i32_16x16x64_i8 v[74:77], v[154:157], v[194:197], 0
	v_mfma_i32_16x16x64_i8 v[98:101], v[146:149], v[202:205], 0
	v_mfma_i32_16x16x64_i8 v[66:69], v[154:157], v[202:205], 0
	v_mfma_i32_16x16x64_i8 v[90:93], v[146:149], v[210:213], 0
	v_mfma_i32_16x16x64_i8 v[58:61], v[154:157], v[210:213], 0
	v_mfma_i32_16x16x64_i8 v[118:121], v[150:153], v[190:193], v[118:121]
	v_mfma_i32_16x16x64_i8 v[82:85], v[158:161], v[190:193], v[82:85]
	v_mfma_i32_16x16x64_i8 v[110:113], v[150:153], v[198:201], v[110:113]
	v_mfma_i32_16x16x64_i8 v[74:77], v[158:161], v[198:201], v[74:77]
	v_mfma_i32_16x16x64_i8 v[98:101], v[150:153], v[206:209], v[98:101]
	v_mfma_i32_16x16x64_i8 v[66:69], v[158:161], v[206:209], v[66:69]
	v_mfma_i32_16x16x64_i8 v[90:93], v[150:153], v[214:217], v[90:93]
	v_mfma_i32_16x16x64_i8 v[58:61], v[158:161], v[214:217], v[58:61]
	s_barrier
	s_add_i32 s70, s92, s77
	v_lshl_add_u64 v[166:167], s[62:63], 0, v[170:171]
	s_mov_b32 m0, s70
	ds_read_b128 v[162:165], v250 offset:16384
	ds_read_b128 v[190:193], v250 offset:17408
	ds_read_b128 v[194:197], v250 offset:18432
	ds_read_b128 v[198:201], v250 offset:19456
	ds_read_b128 v[202:205], v250 offset:20480
	ds_read_b128 v[206:209], v250 offset:21504
	ds_read_b128 v[210:213], v250 offset:22528
	ds_read_b128 v[214:217], v250 offset:23552
	global_load_lds_dwordx4 v[166:167], off
	s_add_i32 m0, s70, 0x2000
	s_add_u32 s70, s62, 0x80000
	v_lshl_add_u64 v[218:219], s[62:63], 0, v[174:175]
	s_addc_u32 s71, s63, 0
	s_add_i32 s72, s93, s77
	global_load_lds_dwordx4 v[218:219], off
	v_lshl_add_u64 v[220:221], s[70:71], 0, v[170:171]
	s_mov_b32 m0, s72
	v_lshl_add_u64 v[222:223], s[66:67], 0, v[172:173]
	global_load_lds_dwordx4 v[220:221], off
	v_lshl_add_u64 v[220:221], s[70:71], 0, v[174:175]
	s_add_i32 m0, s72, 0x2000
	s_nop 0
	global_load_lds_dwordx4 v[220:221], off
	v_lshl_add_u64 v[220:221], s[66:67], 0, v[168:169]
	s_mov_b32 m0, s78
	s_nop 0
	global_load_lds_dwordx4 v[220:221], off
	s_mov_b32 m0, s79
	s_nop 0
	global_load_lds_dwordx4 v[222:223], off
	s_waitcnt vmcnt(8)
	s_waitcnt lgkmcnt(0)
	s_barrier
	v_mfma_i32_16x16x64_i8 v[70:73], v[130:133], v[162:165], 0
	v_mfma_i32_16x16x64_i8 v[62:65], v[138:141], v[162:165], 0
	v_mfma_i32_16x16x64_i8 v[38:41], v[130:133], v[194:197], 0
	v_mfma_i32_16x16x64_i8 v[54:57], v[138:141], v[194:197], 0
	v_mfma_i32_16x16x64_i8 v[30:33], v[130:133], v[202:205], 0
	v_mfma_i32_16x16x64_i8 v[50:53], v[138:141], v[202:205], 0
	v_mfma_i32_16x16x64_i8 v[26:29], v[130:133], v[210:213], 0
	v_mfma_i32_16x16x64_i8 v[18:21], v[138:141], v[210:213], 0
	v_mfma_i32_16x16x64_i8 v[70:73], v[134:137], v[190:193], v[70:73]
	v_mfma_i32_16x16x64_i8 v[62:65], v[142:145], v[190:193], v[62:65]
	v_mfma_i32_16x16x64_i8 v[38:41], v[134:137], v[198:201], v[38:41]
	v_mfma_i32_16x16x64_i8 v[54:57], v[142:145], v[198:201], v[54:57]
	v_mfma_i32_16x16x64_i8 v[30:33], v[134:137], v[206:209], v[30:33]
	v_mfma_i32_16x16x64_i8 v[50:53], v[142:145], v[206:209], v[50:53]
	v_mfma_i32_16x16x64_i8 v[26:29], v[134:137], v[214:217], v[26:29]
	v_mfma_i32_16x16x64_i8 v[18:21], v[142:145], v[214:217], v[18:21]
	v_mfma_i32_16x16x64_i8 v[46:49], v[146:149], v[162:165], 0
	v_mfma_i32_16x16x64_i8 v[14:17], v[154:157], v[162:165], 0
	v_mfma_i32_16x16x64_i8 v[42:45], v[146:149], v[194:197], 0
	v_mfma_i32_16x16x64_i8 v[10:13], v[154:157], v[194:197], 0
	v_mfma_i32_16x16x64_i8 v[34:37], v[146:149], v[202:205], 0
	v_mfma_i32_16x16x64_i8 v[6:9], v[154:157], v[202:205], 0
	v_mfma_i32_16x16x64_i8 v[22:25], v[146:149], v[210:213], 0
	v_mfma_i32_16x16x64_i8 v[2:5], v[154:157], v[210:213], 0
	v_mfma_i32_16x16x64_i8 v[46:49], v[150:153], v[190:193], v[46:49]
	v_mfma_i32_16x16x64_i8 v[14:17], v[158:161], v[190:193], v[14:17]
	v_mfma_i32_16x16x64_i8 v[42:45], v[150:153], v[198:201], v[42:45]
	v_mfma_i32_16x16x64_i8 v[10:13], v[158:161], v[198:201], v[10:13]
	v_mfma_i32_16x16x64_i8 v[34:37], v[150:153], v[206:209], v[34:37]
	v_mfma_i32_16x16x64_i8 v[6:9], v[158:161], v[206:209], v[6:9]
	v_mfma_i32_16x16x64_i8 v[22:25], v[150:153], v[214:217], v[22:25]
	v_mfma_i32_16x16x64_i8 v[2:5], v[158:161], v[214:217], v[2:5]
	s_barrier
; #define PG8_STAGE(bufoff, gbase, voff) do { _Pragma("unroll") for (int _i = 0; _i < 2; ++_i) \
;         __builtin_amdgcn_global_load_lds((const unsigned*)((const char*)(gbase) + (voff)[_i]), (LAS unsigned*)(lds + (bufoff) + ldsw + _i * 8192), 16, 0, 0); } while (0)
; #define PG8_LDA(dst, b, h) do { _Pragma("unroll") for (int m = 0; m < 4; ++m) _Pragma("unroll") for (int k = 0; k < 2; ++k) dst[m][k] = *(const LAS bf16x8*)(lds + PG8_SA(b, h) + aoff + m * 2048 + k * 1024); } while (0)
; #define PG8_LDB(dst, b, h) do { _Pragma("unroll") for (int n = 0; n < 2; ++n) _Pragma("unroll") for (int k = 0; k < 2; ++k) dst[n][k] = *(const LAS bf16x8*)(lds + PG8_SB(b, h) + boff + n * 2048 + k * 1024); } while (0)
; #define PG8_WAIT_V(n) asm volatile("s_waitcnt vmcnt(" #n ")" ::: "memory")
; #define PG8_WAIT_L(n) asm volatile("s_waitcnt lgkmcnt(" #n ")" ::: "memory")
; #define PG8_BAR __builtin_amdgcn_s_barrier()
; #define PG8_SCHED __builtin_amdgcn_sched_barrier(0)
; template <class Epi, class Geom, class Sched, bool ALIGN_EPI, bool I8 = false>
; __device__ __forceinline__ void gemm_phase(LAS unsigned char* lds, const Gemm g, const Sched& S, const Epi& E) {
;     ...
;             PG8_LDB(B0, 1, 0); PG8_LDB(B1, 1, 1); PG8_SCHED; PG8_LDA(At, 1, 0); PG8_STAGE(PG8_SA(0, 1), a2 + hsA, voffA);
;             PG8_WAIT_V(8); PG8_WAIT_L(0); PG8_BAR; PG8_MMA(0, 0, At, B0); PG8_MMA(0, 1, At, B1); PG8_BAR; PG8_SCHED;
;             PG8_LDA(At, 1, 1); PG8_STAGE(PG8_SB(1, 0), b3, voffB); PG8_STAGE(PG8_SB(1, 1), b3 + hsB, voffB); PG8_STAGE(PG8_SA(1, 0), a3, voffA);
;             PG8_WAIT_V(8); PG8_WAIT_L(0); PG8_BAR; PG8_MMA(1, 0, At, B0); PG8_MMA(1, 1, At, B1); PG8_BAR; PG8_SCHED;
;         }
	s_add_i32 s70, 0, 0x18000
	s_add_i32 s71, 0, 0x1c000
	v_add_u32_e32 v142, s70, v1
	v_add_u32_e32 v158, s71, v1
	ds_read_b128 v[130:133], v142
	ds_read_b128 v[134:137], v142 offset:1024
	ds_read_b128 v[138:141], v142 offset:2048
	ds_read_b128 v[142:145], v142 offset:3072
	ds_read_b128 v[146:149], v158
	ds_read_b128 v[150:153], v158 offset:1024
	ds_read_b128 v[154:157], v158 offset:2048
	ds_read_b128 v[158:161], v158 offset:3072
	s_add_u32 s66, s66, 0x80000
	s_addc_u32 s67, s67, 0
	s_mov_b32 m0, s80
	v_lshl_add_u64 v[224:225], s[66:67], 0, v[168:169]
	ds_read_b128 v[162:165], v250 offset:32768
	ds_read_b128 v[190:193], v250 offset:33792
	ds_read_b128 v[194:197], v250 offset:34816
	ds_read_b128 v[198:201], v250 offset:35840
	ds_read_b128 v[202:205], v250 offset:36864
	ds_read_b128 v[206:209], v250 offset:37888
	ds_read_b128 v[210:213], v250 offset:38912
	ds_read_b128 v[214:217], v250 offset:39936
	global_load_lds_dwordx4 v[224:225], off
	v_lshl_add_u64 v[224:225], s[66:67], 0, v[172:173]
	s_mov_b32 m0, s81
	s_nop 0
	global_load_lds_dwordx4 v[224:225], off
	s_waitcnt vmcnt(8)
	s_waitcnt lgkmcnt(0)
	s_barrier
	v_mfma_i32_16x16x64_i8 v[126:129], v[130:133], v[162:165], v[126:129]
	v_mfma_i32_16x16x64_i8 v[122:125], v[138:141], v[162:165], v[122:125]
	v_mfma_i32_16x16x64_i8 v[114:117], v[130:133], v[194:197], v[114:117]
	v_mfma_i32_16x16x64_i8 v[106:109], v[138:141], v[194:197], v[106:109]
	v_mfma_i32_16x16x64_i8 v[102:105], v[130:133], v[202:205], v[102:105]
	v_mfma_i32_16x16x64_i8 v[94:97], v[138:141], v[202:205], v[94:97]
	v_mfma_i32_16x16x64_i8 v[86:89], v[130:133], v[210:213], v[86:89]
	v_mfma_i32_16x16x64_i8 v[78:81], v[138:141], v[210:213], v[78:81]
	v_mfma_i32_16x16x64_i8 v[126:129], v[134:137], v[190:193], v[126:129]
	v_mfma_i32_16x16x64_i8 v[122:125], v[142:145], v[190:193], v[122:125]
	v_mfma_i32_16x16x64_i8 v[114:117], v[134:137], v[198:201], v[114:117]
	v_mfma_i32_16x16x64_i8 v[106:109], v[142:145], v[198:201], v[106:109]
	v_mfma_i32_16x16x64_i8 v[102:105], v[134:137], v[206:209], v[102:105]
	v_mfma_i32_16x16x64_i8 v[94:97], v[142:145], v[206:209], v[94:97]
	v_mfma_i32_16x16x64_i8 v[86:89], v[134:137], v[214:217], v[86:89]
	v_mfma_i32_16x16x64_i8 v[78:81], v[142:145], v[214:217], v[78:81]
	v_mfma_i32_16x16x64_i8 v[118:121], v[146:149], v[162:165], v[118:121]
	v_mfma_i32_16x16x64_i8 v[82:85], v[154:157], v[162:165], v[82:85]
	v_mfma_i32_16x16x64_i8 v[110:113], v[146:149], v[194:197], v[110:113]
	v_mfma_i32_16x16x64_i8 v[74:77], v[154:157], v[194:197], v[74:77]
	v_mfma_i32_16x16x64_i8 v[98:101], v[146:149], v[202:205], v[98:101]
	v_mfma_i32_16x16x64_i8 v[66:69], v[154:157], v[202:205], v[66:69]
	v_mfma_i32_16x16x64_i8 v[90:93], v[146:149], v[210:213], v[90:93]
	v_mfma_i32_16x16x64_i8 v[58:61], v[154:157], v[210:213], v[58:61]
	v_mfma_i32_16x16x64_i8 v[118:121], v[150:153], v[190:193], v[118:121]
	v_mfma_i32_16x16x64_i8 v[82:85], v[158:161], v[190:193], v[82:85]
	v_mfma_i32_16x16x64_i8 v[110:113], v[150:153], v[198:201], v[110:113]
	v_mfma_i32_16x16x64_i8 v[74:77], v[158:161], v[198:201], v[74:77]
	v_mfma_i32_16x16x64_i8 v[98:101], v[150:153], v[206:209], v[98:101]
	v_mfma_i32_16x16x64_i8 v[66:69], v[158:161], v[206:209], v[66:69]
	v_mfma_i32_16x16x64_i8 v[90:93], v[150:153], v[214:217], v[90:93]
	v_mfma_i32_16x16x64_i8 v[58:61], v[158:161], v[214:217], v[58:61]
	s_barrier
	s_add_i32 s66, s70, s77
	v_lshl_add_u64 v[166:167], v[166:167], 0, s[28:29]
	s_mov_b32 m0, s66
	ds_read_b128 v[162:165], v250 offset:49152
	ds_read_b128 v[190:193], v250 offset:50176
	ds_read_b128 v[194:197], v250 offset:51200
	ds_read_b128 v[198:201], v250 offset:52224
	ds_read_b128 v[202:205], v250 offset:53248
	ds_read_b128 v[206:209], v250 offset:54272
	ds_read_b128 v[210:213], v250 offset:55296
	ds_read_b128 v[214:217], v250 offset:56320
	global_load_lds_dwordx4 v[166:167], off
	s_add_i32 m0, s66, 0x2000
	s_add_u32 s62, s62, 0x80080
	v_lshl_add_u64 v[166:167], v[218:219], 0, s[28:29]
	s_addc_u32 s63, s63, 0
	s_add_i32 s66, s71, s77
	global_load_lds_dwordx4 v[166:167], off
	v_lshl_add_u64 v[166:167], s[62:63], 0, v[170:171]
	s_mov_b32 m0, s66
	s_nop 0
	global_load_lds_dwordx4 v[166:167], off
	v_lshl_add_u64 v[166:167], s[62:63], 0, v[174:175]
	s_add_i32 m0, s66, 0x2000
	s_nop 0
	global_load_lds_dwordx4 v[166:167], off
	v_lshl_add_u64 v[166:167], v[220:221], 0, s[28:29]
	s_mov_b32 m0, s88
	s_nop 0
	global_load_lds_dwordx4 v[166:167], off
	v_lshl_add_u64 v[166:167], v[222:223], 0, s[28:29]
	s_mov_b32 m0, s89
	s_nop 0
	global_load_lds_dwordx4 v[166:167], off
	s_waitcnt vmcnt(8)
	s_waitcnt lgkmcnt(0)
	s_barrier
	v_mfma_i32_16x16x64_i8 v[70:73], v[130:133], v[162:165], v[70:73]
	v_mfma_i32_16x16x64_i8 v[62:65], v[138:141], v[162:165], v[62:65]
	v_mfma_i32_16x16x64_i8 v[38:41], v[130:133], v[194:197], v[38:41]
	v_mfma_i32_16x16x64_i8 v[54:57], v[138:141], v[194:197], v[54:57]
	v_mfma_i32_16x16x64_i8 v[30:33], v[130:133], v[202:205], v[30:33]
	v_mfma_i32_16x16x64_i8 v[50:53], v[138:141], v[202:205], v[50:53]
	v_mfma_i32_16x16x64_i8 v[26:29], v[130:133], v[210:213], v[26:29]
	v_mfma_i32_16x16x64_i8 v[18:21], v[138:141], v[210:213], v[18:21]
	v_mfma_i32_16x16x64_i8 v[70:73], v[134:137], v[190:193], v[70:73]
	v_mfma_i32_16x16x64_i8 v[62:65], v[142:145], v[190:193], v[62:65]
	v_mfma_i32_16x16x64_i8 v[38:41], v[134:137], v[198:201], v[38:41]
	v_mfma_i32_16x16x64_i8 v[54:57], v[142:145], v[198:201], v[54:57]
	v_mfma_i32_16x16x64_i8 v[30:33], v[134:137], v[206:209], v[30:33]
	v_mfma_i32_16x16x64_i8 v[50:53], v[142:145], v[206:209], v[50:53]
	v_mfma_i32_16x16x64_i8 v[26:29], v[134:137], v[214:217], v[26:29]
	v_mfma_i32_16x16x64_i8 v[18:21], v[142:145], v[214:217], v[18:21]
	v_mfma_i32_16x16x64_i8 v[46:49], v[146:149], v[162:165], v[46:49]
	v_mfma_i32_16x16x64_i8 v[14:17], v[154:157], v[162:165], v[14:17]
	v_mfma_i32_16x16x64_i8 v[42:45], v[146:149], v[194:197], v[42:45]
	v_mfma_i32_16x16x64_i8 v[10:13], v[154:157], v[194:197], v[10:13]
	v_mfma_i32_16x16x64_i8 v[34:37], v[146:149], v[202:205], v[34:37]
	v_mfma_i32_16x16x64_i8 v[6:9], v[154:157], v[202:205], v[6:9]
	v_mfma_i32_16x16x64_i8 v[22:25], v[146:149], v[210:213], v[22:25]
	v_mfma_i32_16x16x64_i8 v[2:5], v[154:157], v[210:213], v[2:5]
	v_mfma_i32_16x16x64_i8 v[46:49], v[150:153], v[190:193], v[46:49]
	v_mfma_i32_16x16x64_i8 v[14:17], v[158:161], v[190:193], v[14:17]
	v_mfma_i32_16x16x64_i8 v[42:45], v[150:153], v[198:201], v[42:45]
	v_mfma_i32_16x16x64_i8 v[10:13], v[158:161], v[198:201], v[10:13]
	v_mfma_i32_16x16x64_i8 v[34:37], v[150:153], v[206:209], v[34:37]
	v_mfma_i32_16x16x64_i8 v[6:9], v[158:161], v[206:209], v[6:9]
	v_mfma_i32_16x16x64_i8 v[22:25], v[150:153], v[214:217], v[22:25]
	v_mfma_i32_16x16x64_i8 v[2:5], v[158:161], v[214:217], v[2:5]
	s_barrier
	s_add_i32 s69, s69, 2
	s_add_u32 s20, s20, 0x100
	s_addc_u32 s21, s21, 0
	s_add_u32 s65, s65, 0x100
	s_addc_u32 s68, s68, 0
	s_cmp_gt_u32 s69, 29
	s_branch .LBB0_2520

; #define PG8_STAGE(bufoff, gbase, voff) do { _Pragma("unroll") for (int _i = 0; _i < 2; ++_i) \
;         __builtin_amdgcn_global_load_lds((const unsigned*)((const char*)(gbase) + (voff)[_i]), (LAS unsigned*)(lds + (bufoff) + ldsw + _i * 8192), 16, 0, 0); } while (0)
; #define PG8_LDA(dst, b, h) do { _Pragma("unroll") for (int m = 0; m < 4; ++m) _Pragma("unroll") for (int k = 0; k < 2; ++k) dst[m][k] = *(const LAS bf16x8*)(lds + PG8_SA(b, h) + aoff + m * 2048 + k * 1024); } while (0)
; #define PG8_LDB(dst, b, h) do { _Pragma("unroll") for (int n = 0; n < 2; ++n) _Pragma("unroll") for (int k = 0; k < 2; ++k) dst[n][k] = *(const LAS bf16x8*)(lds + PG8_SB(b, h) + boff + n * 2048 + k * 1024); } while (0)
; #define PG8_WAIT_V(n) asm volatile("s_waitcnt vmcnt(" #n ")" ::: "memory")
; #define PG8_WAIT_L(n) asm volatile("s_waitcnt lgkmcnt(" #n ")" ::: "memory")
; #define PG8_BAR __builtin_amdgcn_s_barrier()
; #define PG8_SCHED __builtin_amdgcn_sched_barrier(0)
; template <class Epi, class Geom, class Sched, bool ALIGN_EPI, bool I8 = false>
; __device__ __forceinline__ void gemm_phase(LAS unsigned char* lds, const Gemm g, const Sched& S, const Epi& E) {
;     ...
;             PG8_LDB(B0, 0, 0); PG8_LDB(B1, 0, 1); PG8_SCHED; PG8_LDA(At, 0, 0); PG8_STAGE(PG8_SA(1, 1), a1 + hsA, voffA);
;             PG8_WAIT_V(8); PG8_WAIT_L(0); PG8_BAR; PG8_MMA(0, 0, At, B0); PG8_MMA(0, 1, At, B1); PG8_BAR; PG8_SCHED;
;             PG8_LDA(At, 0, 1); PG8_STAGE(PG8_SB(0, 0), b2, voffB); PG8_STAGE(PG8_SB(0, 1), b2 + hsB, voffB); PG8_STAGE(PG8_SA(0, 0), a2, voffA);
;             PG8_WAIT_V(8); PG8_WAIT_L(0); PG8_BAR; PG8_MMA(1, 0, At, B0); PG8_MMA(1, 1, At, B1); PG8_BAR; PG8_SCHED;
.Lpz2_0:
	ds_read_b128 v[90:93], v181
	ds_read_b128 v[98:101], v181 offset:1024
	ds_read_b128 v[102:105], v181 offset:2048
	ds_read_b128 v[160:163], v181 offset:3072
	ds_read_b128 v[182:185], v206
	ds_read_b128 v[186:189], v206 offset:1024
	ds_read_b128 v[190:193], v206 offset:2048
	ds_read_b128 v[194:197], v206 offset:3072
	s_add_u32 s38, s36, 0xffe80080
	s_addc_u32 s39, s37, -1
	s_cmpk_eq_i32 s62, 0x5c
	s_cselect_b32 s41, s1, s39
	s_cselect_b32 s40, s0, s38
	s_cselect_b32 s39, s35, s61
	s_cselect_b32 s38, s34, s60
	v_lshl_add_u64 v[152:153], s[36:37], 0, v[146:147]
	s_add_i32 m0, s33, 0xc000
	ds_read_b128 v[198:201], v207
	ds_read_b128 v[202:205], v207 offset:1024
	ds_read_b128 v[208:211], v207 offset:2048
	ds_read_b128 v[212:215], v207 offset:3072
	ds_read_b128 v[216:219], v207 offset:4096
	ds_read_b128 v[220:223], v207 offset:5120
	ds_read_b128 v[224:227], v207 offset:6144
	ds_read_b128 v[228:231], v207 offset:7168
	global_load_lds_dwordx4 v[152:153], off
	v_lshl_add_u64 v[152:153], s[36:37], 0, v[148:149]
	s_add_i32 m0, s33, 0xe000
	s_nop 0
	global_load_lds_dwordx4 v[152:153], off
	s_waitcnt vmcnt(8)
	s_waitcnt lgkmcnt(0)
	s_barrier
	v_mfma_i32_16x16x64_i8 v[94:97], v[90:93], v[198:201], 0
	v_mfma_i32_16x16x64_i8 v[138:141], v[102:105], v[198:201], 0
	v_mfma_i32_16x16x64_i8 v[130:133], v[90:93], v[208:211], 0
	v_mfma_i32_16x16x64_i8 v[122:125], v[102:105], v[208:211], 0
	v_mfma_i32_16x16x64_i8 v[110:113], v[90:93], v[216:219], 0
	v_mfma_i32_16x16x64_i8 v[106:109], v[102:105], v[216:219], 0
	v_mfma_i32_16x16x64_i8 v[82:85], v[90:93], v[224:227], 0
	v_mfma_i32_16x16x64_i8 v[74:77], v[102:105], v[224:227], 0
	v_mfma_i32_16x16x64_i8 v[94:97], v[98:101], v[202:205], v[94:97]
	v_mfma_i32_16x16x64_i8 v[138:141], v[160:163], v[202:205], v[138:141]
	v_mfma_i32_16x16x64_i8 v[130:133], v[98:101], v[212:215], v[130:133]
	v_mfma_i32_16x16x64_i8 v[122:125], v[160:163], v[212:215], v[122:125]
	v_mfma_i32_16x16x64_i8 v[110:113], v[98:101], v[220:223], v[110:113]
	v_mfma_i32_16x16x64_i8 v[106:109], v[160:163], v[220:223], v[106:109]
	v_mfma_i32_16x16x64_i8 v[82:85], v[98:101], v[228:231], v[82:85]
	v_mfma_i32_16x16x64_i8 v[74:77], v[160:163], v[228:231], v[74:77]
	v_mfma_i32_16x16x64_i8 v[134:137], v[182:185], v[198:201], 0
	v_mfma_i32_16x16x64_i8 v[126:129], v[190:193], v[198:201], 0
	v_mfma_i32_16x16x64_i8 v[118:121], v[182:185], v[208:211], 0
	v_mfma_i32_16x16x64_i8 v[114:117], v[190:193], v[208:211], 0
	v_mfma_i32_16x16x64_i8 v[86:89], v[182:185], v[216:219], 0
	v_mfma_i32_16x16x64_i8 v[78:81], v[190:193], v[216:219], 0
	v_mfma_i32_16x16x64_i8 v[70:73], v[182:185], v[224:227], 0
	v_mfma_i32_16x16x64_i8 v[66:69], v[190:193], v[224:227], 0
	v_mfma_i32_16x16x64_i8 v[134:137], v[186:189], v[202:205], v[134:137]
	v_mfma_i32_16x16x64_i8 v[126:129], v[194:197], v[202:205], v[126:129]
	v_mfma_i32_16x16x64_i8 v[118:121], v[186:189], v[212:215], v[118:121]
	v_mfma_i32_16x16x64_i8 v[114:117], v[194:197], v[212:215], v[114:117]
	v_mfma_i32_16x16x64_i8 v[86:89], v[186:189], v[220:223], v[86:89]
	v_mfma_i32_16x16x64_i8 v[78:81], v[194:197], v[220:223], v[78:81]
	v_mfma_i32_16x16x64_i8 v[70:73], v[186:189], v[228:231], v[70:73]
	v_mfma_i32_16x16x64_i8 v[66:69], v[194:197], v[228:231], v[66:69]
	s_barrier
	s_add_i32 s63, s14, s46
	v_lshl_add_u64 v[152:153], s[38:39], 0, v[144:145]
	s_mov_b32 m0, s63
	ds_read_b128 v[198:201], v207 offset:16384
	ds_read_b128 v[202:205], v207 offset:17408
	ds_read_b128 v[208:211], v207 offset:18432
	ds_read_b128 v[212:215], v207 offset:19456
	ds_read_b128 v[216:219], v207 offset:20480
	ds_read_b128 v[220:223], v207 offset:21504
	ds_read_b128 v[224:227], v207 offset:22528
	ds_read_b128 v[228:231], v207 offset:23552
	global_load_lds_dwordx4 v[152:153], off
	s_add_i32 m0, s63, 0x2000
	s_add_u32 s64, s38, 0x180000
	v_lshl_add_u64 v[156:157], s[38:39], 0, v[142:143]
	s_addc_u32 s65, s39, 0
	s_add_i32 s63, s55, s46
	global_load_lds_dwordx4 v[156:157], off
	v_lshl_add_u64 v[166:167], s[64:65], 0, v[144:145]
	s_mov_b32 m0, s63
	v_lshl_add_u64 v[170:171], s[40:41], 0, v[142:143]
	global_load_lds_dwordx4 v[166:167], off
	v_lshl_add_u64 v[166:167], s[64:65], 0, v[142:143]
	s_add_i32 m0, s63, 0x2000
	s_nop 0
	global_load_lds_dwordx4 v[166:167], off
	v_lshl_add_u64 v[166:167], s[40:41], 0, v[144:145]
	s_mov_b32 m0, s33
	s_nop 0
	global_load_lds_dwordx4 v[166:167], off
	s_mov_b32 m0, s49
	s_nop 0
	global_load_lds_dwordx4 v[170:171], off
	s_waitcnt vmcnt(8)
	s_waitcnt lgkmcnt(0)
	s_barrier
	v_mfma_i32_16x16x64_i8 v[62:65], v[90:93], v[198:201], 0
	v_mfma_i32_16x16x64_i8 v[58:61], v[102:105], v[198:201], 0
	v_mfma_i32_16x16x64_i8 v[50:53], v[90:93], v[208:211], 0
	v_mfma_i32_16x16x64_i8 v[42:45], v[102:105], v[208:211], 0
	v_mfma_i32_16x16x64_i8 v[30:33], v[90:93], v[216:219], 0
	v_mfma_i32_16x16x64_i8 v[26:29], v[102:105], v[216:219], 0
	v_mfma_i32_16x16x64_i8 v[18:21], v[90:93], v[224:227], 0
	v_mfma_i32_16x16x64_i8 v[10:13], v[102:105], v[224:227], 0
	v_mfma_i32_16x16x64_i8 v[62:65], v[98:101], v[202:205], v[62:65]
	v_mfma_i32_16x16x64_i8 v[58:61], v[160:163], v[202:205], v[58:61]
	v_mfma_i32_16x16x64_i8 v[50:53], v[98:101], v[212:215], v[50:53]
	v_mfma_i32_16x16x64_i8 v[42:45], v[160:163], v[212:215], v[42:45]
	v_mfma_i32_16x16x64_i8 v[30:33], v[98:101], v[220:223], v[30:33]
	v_mfma_i32_16x16x64_i8 v[26:29], v[160:163], v[220:223], v[26:29]
	v_mfma_i32_16x16x64_i8 v[18:21], v[98:101], v[228:231], v[18:21]
	v_mfma_i32_16x16x64_i8 v[10:13], v[160:163], v[228:231], v[10:13]
	v_mfma_i32_16x16x64_i8 v[54:57], v[182:185], v[198:201], 0
	v_mfma_i32_16x16x64_i8 v[46:49], v[190:193], v[198:201], 0
	v_mfma_i32_16x16x64_i8 v[38:41], v[182:185], v[208:211], 0
	v_mfma_i32_16x16x64_i8 v[34:37], v[190:193], v[208:211], 0
	v_mfma_i32_16x16x64_i8 v[22:25], v[182:185], v[216:219], 0
	v_mfma_i32_16x16x64_i8 v[14:17], v[190:193], v[216:219], 0
	v_mfma_i32_16x16x64_i8 v[6:9], v[182:185], v[224:227], 0
	v_mfma_i32_16x16x64_i8 v[2:5], v[190:193], v[224:227], 0
	v_mfma_i32_16x16x64_i8 v[54:57], v[186:189], v[202:205], v[54:57]
	v_mfma_i32_16x16x64_i8 v[46:49], v[194:197], v[202:205], v[46:49]
	v_mfma_i32_16x16x64_i8 v[38:41], v[186:189], v[212:215], v[38:41]
	v_mfma_i32_16x16x64_i8 v[34:37], v[194:197], v[212:215], v[34:37]
	v_mfma_i32_16x16x64_i8 v[22:25], v[186:189], v[220:223], v[22:25]
	v_mfma_i32_16x16x64_i8 v[14:17], v[194:197], v[220:223], v[14:17]
	v_mfma_i32_16x16x64_i8 v[6:9], v[186:189], v[228:231], v[6:9]
	v_mfma_i32_16x16x64_i8 v[2:5], v[194:197], v[228:231], v[2:5]
	s_barrier
; #define PG8_STAGE(bufoff, gbase, voff) do { _Pragma("unroll") for (int _i = 0; _i < 2; ++_i) \
;         __builtin_amdgcn_global_load_lds((const unsigned*)((const char*)(gbase) + (voff)[_i]), (LAS unsigned*)(lds + (bufoff) + ldsw + _i * 8192), 16, 0, 0); } while (0)
; #define PG8_LDA(dst, b, h) do { _Pragma("unroll") for (int m = 0; m < 4; ++m) _Pragma("unroll") for (int k = 0; k < 2; ++k) dst[m][k] = *(const LAS bf16x8*)(lds + PG8_SA(b, h) + aoff + m * 2048 + k * 1024); } while (0)
; #define PG8_LDB(dst, b, h) do { _Pragma("unroll") for (int n = 0; n < 2; ++n) _Pragma("unroll") for (int k = 0; k < 2; ++k) dst[n][k] = *(const LAS bf16x8*)(lds + PG8_SB(b, h) + boff + n * 2048 + k * 1024); } while (0)
; #define PG8_WAIT_V(n) asm volatile("s_waitcnt vmcnt(" #n ")" ::: "memory")
; #define PG8_WAIT_L(n) asm volatile("s_waitcnt lgkmcnt(" #n ")" ::: "memory")
; #define PG8_BAR __builtin_amdgcn_s_barrier()
; #define PG8_SCHED __builtin_amdgcn_sched_barrier(0)
; template <class Epi, class Geom, class Sched, bool ALIGN_EPI, bool I8 = false>
; __device__ __forceinline__ void gemm_phase(LAS unsigned char* lds, const Gemm g, const Sched& S, const Epi& E) {
;     ...
;             PG8_LDB(B0, 1, 0); PG8_LDB(B1, 1, 1); PG8_SCHED; PG8_LDA(At, 1, 0); PG8_STAGE(PG8_SA(0, 1), a2 + hsA, voffA);
;             PG8_WAIT_V(8); PG8_WAIT_L(0); PG8_BAR; PG8_MMA(0, 0, At, B0); PG8_MMA(0, 1, At, B1); PG8_BAR; PG8_SCHED;
;             PG8_LDA(At, 1, 1); PG8_STAGE(PG8_SB(1, 0), b3, voffB); PG8_STAGE(PG8_SB(1, 1), b3 + hsB, voffB); PG8_STAGE(PG8_SA(1, 0), a3, voffA);
;             PG8_WAIT_V(8); PG8_WAIT_L(0); PG8_BAR; PG8_MMA(1, 0, At, B0); PG8_MMA(1, 1, At, B1); PG8_BAR; PG8_SCHED;
;         }
	s_add_i32 s63, 0, 0x18000
	v_add_u32_e32 v154, s63, v175
	s_add_i32 s64, 0, 0x1c000
	ds_read_b128 v[90:93], v154
	ds_read_b128 v[98:101], v154 offset:1024
	ds_read_b128 v[102:105], v154 offset:2048
	ds_read_b128 v[160:163], v154 offset:3072
	v_add_u32_e32 v154, s64, v175
	ds_read_b128 v[182:185], v154
	ds_read_b128 v[186:189], v154 offset:1024
	ds_read_b128 v[190:193], v154 offset:2048
	ds_read_b128 v[194:197], v154 offset:3072
	s_add_u32 s40, s40, 0x180000
	s_addc_u32 s41, s41, 0
	s_mov_b32 m0, s50
	v_lshl_add_u64 v[176:177], s[40:41], 0, v[144:145]
	ds_read_b128 v[198:201], v207 offset:32768
	ds_read_b128 v[202:205], v207 offset:33792
	ds_read_b128 v[208:211], v207 offset:34816
	ds_read_b128 v[212:215], v207 offset:35840
	ds_read_b128 v[216:219], v207 offset:36864
	ds_read_b128 v[220:223], v207 offset:37888
	ds_read_b128 v[224:227], v207 offset:38912
	ds_read_b128 v[228:231], v207 offset:39936
	global_load_lds_dwordx4 v[176:177], off
	v_lshl_add_u64 v[176:177], s[40:41], 0, v[142:143]
	s_mov_b32 m0, s51
	s_nop 0
	global_load_lds_dwordx4 v[176:177], off
	s_waitcnt vmcnt(8)
	s_waitcnt lgkmcnt(0)
	s_barrier
	v_mfma_i32_16x16x64_i8 v[94:97], v[90:93], v[198:201], v[94:97]
	v_mfma_i32_16x16x64_i8 v[138:141], v[102:105], v[198:201], v[138:141]
	v_mfma_i32_16x16x64_i8 v[130:133], v[90:93], v[208:211], v[130:133]
	v_mfma_i32_16x16x64_i8 v[122:125], v[102:105], v[208:211], v[122:125]
	v_mfma_i32_16x16x64_i8 v[110:113], v[90:93], v[216:219], v[110:113]
	v_mfma_i32_16x16x64_i8 v[106:109], v[102:105], v[216:219], v[106:109]
	v_mfma_i32_16x16x64_i8 v[82:85], v[90:93], v[224:227], v[82:85]
	v_mfma_i32_16x16x64_i8 v[74:77], v[102:105], v[224:227], v[74:77]
	v_mfma_i32_16x16x64_i8 v[94:97], v[98:101], v[202:205], v[94:97]
	v_mfma_i32_16x16x64_i8 v[138:141], v[160:163], v[202:205], v[138:141]
	v_mfma_i32_16x16x64_i8 v[130:133], v[98:101], v[212:215], v[130:133]
	v_mfma_i32_16x16x64_i8 v[122:125], v[160:163], v[212:215], v[122:125]
	v_mfma_i32_16x16x64_i8 v[110:113], v[98:101], v[220:223], v[110:113]
	v_mfma_i32_16x16x64_i8 v[106:109], v[160:163], v[220:223], v[106:109]
	v_mfma_i32_16x16x64_i8 v[82:85], v[98:101], v[228:231], v[82:85]
	v_mfma_i32_16x16x64_i8 v[74:77], v[160:163], v[228:231], v[74:77]
	v_mfma_i32_16x16x64_i8 v[134:137], v[182:185], v[198:201], v[134:137]
	v_mfma_i32_16x16x64_i8 v[126:129], v[190:193], v[198:201], v[126:129]
	v_mfma_i32_16x16x64_i8 v[118:121], v[182:185], v[208:211], v[118:121]
	v_mfma_i32_16x16x64_i8 v[114:117], v[190:193], v[208:211], v[114:117]
	v_mfma_i32_16x16x64_i8 v[86:89], v[182:185], v[216:219], v[86:89]
	v_mfma_i32_16x16x64_i8 v[78:81], v[190:193], v[216:219], v[78:81]
	v_mfma_i32_16x16x64_i8 v[70:73], v[182:185], v[224:227], v[70:73]
	v_mfma_i32_16x16x64_i8 v[66:69], v[190:193], v[224:227], v[66:69]
	v_mfma_i32_16x16x64_i8 v[134:137], v[186:189], v[202:205], v[134:137]
	v_mfma_i32_16x16x64_i8 v[126:129], v[194:197], v[202:205], v[126:129]
	v_mfma_i32_16x16x64_i8 v[118:121], v[186:189], v[212:215], v[118:121]
	v_mfma_i32_16x16x64_i8 v[114:117], v[194:197], v[212:215], v[114:117]
	v_mfma_i32_16x16x64_i8 v[86:89], v[186:189], v[220:223], v[86:89]
	v_mfma_i32_16x16x64_i8 v[78:81], v[194:197], v[220:223], v[78:81]
	v_mfma_i32_16x16x64_i8 v[70:73], v[186:189], v[228:231], v[70:73]
	v_mfma_i32_16x16x64_i8 v[66:69], v[194:197], v[228:231], v[66:69]
	s_barrier
	s_add_i32 s40, s63, s46
	v_lshl_add_u64 v[152:153], v[152:153], 0, s[20:21]
	s_mov_b32 m0, s40
	ds_read_b128 v[198:201], v207 offset:49152
	ds_read_b128 v[202:205], v207 offset:50176
	ds_read_b128 v[208:211], v207 offset:51200
	ds_read_b128 v[212:215], v207 offset:52224
	ds_read_b128 v[216:219], v207 offset:53248
	ds_read_b128 v[220:223], v207 offset:54272
	ds_read_b128 v[224:227], v207 offset:55296
	ds_read_b128 v[228:231], v207 offset:56320
	global_load_lds_dwordx4 v[152:153], off
	s_add_i32 m0, s40, 0x2000
	s_add_u32 s38, s38, 0x180080
	v_lshl_add_u64 v[152:153], v[156:157], 0, s[20:21]
	s_addc_u32 s39, s39, 0
	s_add_i32 s40, s64, s46
	global_load_lds_dwordx4 v[152:153], off
	v_lshl_add_u64 v[152:153], s[38:39], 0, v[144:145]
	s_mov_b32 m0, s40
	s_nop 0
	global_load_lds_dwordx4 v[152:153], off
	v_lshl_add_u64 v[152:153], s[38:39], 0, v[142:143]
	s_add_i32 m0, s40, 0x2000
	s_nop 0
	global_load_lds_dwordx4 v[152:153], off
	v_lshl_add_u64 v[152:153], v[166:167], 0, s[20:21]
	s_mov_b32 m0, s52
	s_nop 0
	global_load_lds_dwordx4 v[152:153], off
	v_lshl_add_u64 v[152:153], v[170:171], 0, s[20:21]
	s_mov_b32 m0, s53
	s_nop 0
	global_load_lds_dwordx4 v[152:153], off
	s_waitcnt vmcnt(8)
	s_waitcnt lgkmcnt(0)
	s_barrier
	v_mfma_i32_16x16x64_i8 v[62:65], v[90:93], v[198:201], v[62:65]
	v_mfma_i32_16x16x64_i8 v[58:61], v[102:105], v[198:201], v[58:61]
	v_mfma_i32_16x16x64_i8 v[50:53], v[90:93], v[208:211], v[50:53]
	v_mfma_i32_16x16x64_i8 v[42:45], v[102:105], v[208:211], v[42:45]
	v_mfma_i32_16x16x64_i8 v[30:33], v[90:93], v[216:219], v[30:33]
	v_mfma_i32_16x16x64_i8 v[26:29], v[102:105], v[216:219], v[26:29]
	v_mfma_i32_16x16x64_i8 v[18:21], v[90:93], v[224:227], v[18:21]
	v_mfma_i32_16x16x64_i8 v[10:13], v[102:105], v[224:227], v[10:13]
	v_mfma_i32_16x16x64_i8 v[62:65], v[98:101], v[202:205], v[62:65]
	v_mfma_i32_16x16x64_i8 v[58:61], v[160:163], v[202:205], v[58:61]
	v_mfma_i32_16x16x64_i8 v[50:53], v[98:101], v[212:215], v[50:53]
	v_mfma_i32_16x16x64_i8 v[42:45], v[160:163], v[212:215], v[42:45]
	v_mfma_i32_16x16x64_i8 v[30:33], v[98:101], v[220:223], v[30:33]
	v_mfma_i32_16x16x64_i8 v[26:29], v[160:163], v[220:223], v[26:29]
	v_mfma_i32_16x16x64_i8 v[18:21], v[98:101], v[228:231], v[18:21]
	v_mfma_i32_16x16x64_i8 v[10:13], v[160:163], v[228:231], v[10:13]
	v_mfma_i32_16x16x64_i8 v[54:57], v[182:185], v[198:201], v[54:57]
	v_mfma_i32_16x16x64_i8 v[46:49], v[190:193], v[198:201], v[46:49]
	v_mfma_i32_16x16x64_i8 v[38:41], v[182:185], v[208:211], v[38:41]
	v_mfma_i32_16x16x64_i8 v[34:37], v[190:193], v[208:211], v[34:37]
	v_mfma_i32_16x16x64_i8 v[22:25], v[182:185], v[216:219], v[22:25]
	v_mfma_i32_16x16x64_i8 v[14:17], v[190:193], v[216:219], v[14:17]
	v_mfma_i32_16x16x64_i8 v[6:9], v[182:185], v[224:227], v[6:9]
	v_mfma_i32_16x16x64_i8 v[2:5], v[190:193], v[224:227], v[2:5]
	v_mfma_i32_16x16x64_i8 v[54:57], v[186:189], v[202:205], v[54:57]
	v_mfma_i32_16x16x64_i8 v[46:49], v[194:197], v[202:205], v[46:49]
	v_mfma_i32_16x16x64_i8 v[38:41], v[186:189], v[212:215], v[38:41]
	v_mfma_i32_16x16x64_i8 v[34:37], v[194:197], v[212:215], v[34:37]
	v_mfma_i32_16x16x64_i8 v[22:25], v[186:189], v[220:223], v[22:25]
	v_mfma_i32_16x16x64_i8 v[14:17], v[194:197], v[220:223], v[14:17]
	v_mfma_i32_16x16x64_i8 v[6:9], v[186:189], v[228:231], v[6:9]
	v_mfma_i32_16x16x64_i8 v[2:5], v[194:197], v[228:231], v[2:5]
	s_barrier
	s_add_i32 s62, s62, 2
	s_add_u32 s36, s36, 0x100
	s_addc_u32 s37, s37, 0
	s_add_u32 s60, s60, 0x100
	s_addc_u32 s61, s61, 0
	s_cmpk_gt_u32 s62, 0x5d
	s_branch .LBB0_2872
